# hand-written ffn_fixup (wave per edge row, batched dwordx4 loads); attnA mask as 16 selects; GEMM-down tile order mirrored
# speedup vs baseline: 1.0855x; 1.0409x over previous
; __device__ __forceinline__ int tidx() { int t = threadIdx.x; asm volatile("" : "+v"(t)); return t; }
; __device__ __forceinline__ void ffn_fixup(const Args& a, int L, int panel) {
;     const float* EP = (const float*)(a.ws + OFF_EP); const float* EG = (const float*)(a.ws + OFF_EG); const float* EU = (const float*)(a.ws + OFF_EU);
;     bf16_t* ACT = (bf16_t*)(a.ws + WS_P);
;     const float* cw = a.in[21] + (size_t)L * 3 * FF;
;     int tid0 = tidx(); asm volatile("" : "+v"(tid0));
;     for (int i = tid0; i < 8 * FF; i += 512) {
;         const int e = i / FF, c = i % FF, gi = 4 * panel + (e >> 1), side = e & 1;
;         const int row = 64 * gi + (side ? 63 : 0);
;         const size_t eo = ((size_t)gi * 2 + side) * FF + c;
; __device__ __forceinline__ void run_phase(const Args& a0, int ph, LAS unsigned char* lds) {
;     Args a = a0;
; #pragma unroll
;     for (int i = 0; i < 24; ++i) { const __attribute__((address_space(1))) float* p = (const __attribute__((address_space(1))) float*)a0.in[i]; asm volatile("" : "+s"(p)); a.in[i] = (const float*)p; }
;     { __attribute__((address_space(1))) float* p = (__attribute__((address_space(1))) float*)a0.out; asm volatile("" : "+s"(p)); a.out = (float*)p; }
;     { __attribute__((address_space(1))) unsigned char* p = (__attribute__((address_space(1))) unsigned char*)a0.ws; asm volatile("" : "+s"(p)); a.ws = (unsigned char*)p; }
;     int G = gridDim.x, c = blockIdx.x; asm volatile("" : "+s"(G), "+s"(c));
;     ...
;     if (ph == 0) { for (int rep = 0; rep < NREP(32); ++rep) { phase0(a, lds); __syncthreads(); } return; }
;     const int L = (ph - 1) / 7, sub = (ph - 1) % 7;
;     bf16_t* H = (bf16_t*)(a.ws + WS_H);
;     bf16_t* Fb = (bf16_t*)(a.ws + WS_F);
;     if (sub == 0) {
.LBB0_11:
	v_readlane_b32 s80, v253, 34
	v_readlane_b32 s81, v253, 35
	s_mov_b64 s[0:1], s[80:81]
	v_readlane_b32 s82, v253, 36
	v_readlane_b32 s83, v253, 37
	v_writelane_b32 v254, s0, 23
	v_readlane_b32 s84, v253, 38
	v_readlane_b32 s85, v253, 39
	v_writelane_b32 v254, s1, 24
	s_mov_b64 s[0:1], s[82:83]
	v_readlane_b32 s86, v253, 40
	v_readlane_b32 s87, v253, 41
	v_readlane_b32 s88, v253, 42
	v_readlane_b32 s89, v253, 43
	v_readlane_b32 s90, v253, 44
	v_readlane_b32 s91, v253, 45
	v_writelane_b32 v254, s0, 25
	s_mov_b64 s[22:23], s[84:85]
	s_mov_b64 s[2:3], s[86:87]
	v_writelane_b32 v254, s1, 26
	s_mov_b64 s[4:5], s[88:89]
	s_mov_b64 s[0:1], s[90:91]
	v_readlane_b32 s92, v253, 46
	v_readlane_b32 s93, v253, 47
	v_writelane_b32 v254, s0, 27
	v_readlane_b32 s94, v253, 48
	v_readlane_b32 s95, v253, 49
	v_writelane_b32 v254, s1, 28
	s_mov_b64 s[0:1], s[92:93]
	s_cmp_lg_u32 s76, 0
	v_writelane_b32 v254, s0, 29
	s_nop 1
	v_writelane_b32 v254, s1, 30
	s_mov_b64 s[0:1], s[94:95]
	v_readlane_b32 s80, v253, 50
	v_writelane_b32 v254, s0, 31
	v_readlane_b32 s81, v253, 51
	v_readlane_b32 s82, v253, 52
	v_writelane_b32 v254, s1, 32
	s_mov_b64 s[0:1], s[80:81]
	v_readlane_b32 s83, v253, 53
	v_readlane_b32 s84, v253, 54
	v_readlane_b32 s85, v253, 55
	v_readlane_b32 s86, v253, 56
	v_readlane_b32 s87, v253, 57
	v_readlane_b32 s94, v254, 0
	v_readlane_b32 s95, v254, 1
	v_writelane_b32 v254, s0, 33
	s_mov_b64 s[18:19], s[82:83]
	s_mov_b64 s[16:17], s[84:85]
	v_writelane_b32 v254, s1, 34
	s_mov_b64 s[0:1], s[86:87]
	v_readlane_b32 s88, v253, 58
	v_readlane_b32 s89, v253, 59
	v_writelane_b32 v254, s0, 35
	v_readlane_b32 s90, v253, 60
	v_readlane_b32 s91, v253, 61
	v_writelane_b32 v254, s1, 36
	s_mov_b64 s[0:1], s[88:89]
	v_readlane_b32 s92, v253, 62
	v_writelane_b32 v254, s0, 37
	v_readlane_b32 s93, v253, 63
	s_nop 0
	v_writelane_b32 v254, s1, 38
	s_mov_b64 s[0:1], s[90:91]
	s_nop 0
	v_writelane_b32 v254, s0, 39
	s_nop 1
	v_writelane_b32 v254, s1, 40
	s_mov_b64 s[0:1], s[92:93]
	s_nop 0
	v_writelane_b32 v254, s0, 41
	s_nop 1
	v_writelane_b32 v254, s1, 42
	s_mov_b64 s[0:1], s[94:95]
	s_nop 0
	v_writelane_b32 v254, s0, 43
	s_nop 1
	v_writelane_b32 v254, s1, 44
	s_nop 0
	v_readlane_b32 s80, v254, 2
	v_readlane_b32 s81, v254, 3
	s_mov_b64 s[0:1], s[80:81]
	v_readlane_b32 s82, v254, 4
	v_readlane_b32 s83, v254, 5
	v_readlane_b32 s84, v254, 6
	v_readlane_b32 s85, v254, 7
	v_readlane_b32 s86, v254, 8
	v_readlane_b32 s87, v254, 9
	v_readlane_b32 s88, v254, 10
	v_readlane_b32 s89, v254, 11
	v_readlane_b32 s90, v254, 12
	v_readlane_b32 s91, v254, 13
	v_readlane_b32 s92, v254, 14
	v_readlane_b32 s93, v254, 15
	v_readlane_b32 s94, v254, 16
	v_readlane_b32 s95, v254, 17
	v_writelane_b32 v254, s0, 45
	s_mov_b64 s[14:15], s[84:85]
	s_mov_b64 s[10:11], s[90:91]
	v_writelane_b32 v254, s1, 46
	s_mov_b64 s[0:1], s[82:83]
	s_mov_b64 s[82:83], s[86:87]
	v_writelane_b32 v254, s0, 47
	s_mov_b64 s[8:9], s[92:93]
	s_mov_b64 s[84:85], s[94:95]
	v_writelane_b32 v254, s1, 48
	s_mov_b64 s[0:1], s[88:89]
	s_mov_b64 s[80:81], s[74:75]
	v_writelane_b32 v254, s0, 49
	s_mov_b32 s88, s60
	s_nop 0
	v_writelane_b32 v254, s1, 50
	s_mov_b64 s[0:1], s[72:73]
	s_nop 0
	v_writelane_b32 v254, s0, 51
	s_nop 1
	v_writelane_b32 v254, s1, 52
	v_readlane_b32 s0, v253, 2
	v_readlane_b32 s1, v253, 3
	s_load_dword s87, s[0:1], 0x0
	s_cselect_b64 s[0:1], -1, 0
	v_writelane_b32 v254, s0, 53
	s_and_b64 vcc, exec, s[0:1]
	s_waitcnt lgkmcnt(0)
	s_mov_b32 s86, s87
	v_writelane_b32 v254, s1, 54
	v_writelane_b32 v254, s80, 55
	s_mov_b64 s[0:1], -1
	s_nop 0
	v_writelane_b32 v254, s81, 56
	s_cbranch_vccz .LBB0_336
	s_add_i32 s0, s76, -1
	s_mul_hi_i32 s1, s0, 0x92492493
	v_writelane_b32 v254, s4, 57
	s_add_i32 s1, s1, s0
	s_mov_b64 s[92:93], s[20:21]
	v_writelane_b32 v254, s5, 58
	s_lshr_b32 s4, s1, 31
	s_ashr_i32 s1, s1, 2
	s_add_i32 s6, s1, s4
	s_mul_i32 s1, s6, 7
	s_sub_i32 s59, s0, s1
	s_mov_b32 s4, s6
	s_add_u32 s90, s80, 0x3f8a000
	v_writelane_b32 v254, s4, 59
	s_addc_u32 s91, s81, 0
	s_add_u32 s94, s80, 0x29f8a000
	v_writelane_b32 v254, s5, 60
	s_mov_b64 s[4:5], 0
	s_addc_u32 s95, s81, 0
	v_writelane_b32 v254, s4, 61
	s_mov_b64 s[0:1], -1
	s_mov_b64 s[20:21], 0
	s_cmp_lt_i32 s59, 3
	v_writelane_b32 v254, s5, 62
	s_cbranch_scc1 .LBB0_137
	s_cmp_gt_i32 s59, 3
	s_cbranch_scc0 .LBB0_39
	s_cmp_gt_i32 s59, 4
	s_cbranch_scc0 .LBB0_40
	s_cmp_eq_u32 s59, 5
	s_cbranch_scc0 .LBB0_66
	s_add_u32 s12, s80, 0xbf8a000
	s_addc_u32 s13, s81, 0
	s_ashr_i32 s33, s86, 31
	s_ashr_i32 s40, s88, 31
	s_add_u32 s0, s80, 0x21f8a000
	s_addc_u32 s1, s81, 0
	s_add_u32 s4, s80, 0x2358a000
	s_addc_u32 s5, s81, 0
	v_readlane_b32 s24, v254, 59
	s_add_u32 s6, s80, 0x24b8a000
	v_readlane_b32 s25, v254, 60
	s_addc_u32 s7, s81, 0
	s_mul_hi_i32 s25, s24, 0x8400
	s_mul_i32 s24, s24, 0x8400
	s_add_u32 s24, s10, s24
	s_addc_u32 s25, s11, s25
	s_cmpk_lg_i32 s86, 0x100
	s_cbranch_scc1 .Lfx_orig
	v_lshrrev_b32_e32 v48, 6, v225
	v_and_b32_e32 v49, 63, v225
	v_lshlrev_b32_e32 v50, 4, v49
	v_lshlrev_b32_e32 v51, 3, v49
	v_readfirstlane_b32 s42, v48
	s_and_b32 s46, s42, 1
	s_lshr_b32 s42, s42, 1
	s_mul_i32 s31, s46, 0x5800
	v_add_u32_e32 v52, s31, v50
	v_add_u32_e32 v53, 0x0, v52
	global_load_dwordx4 v[64:67], v53, s[24:25]
	v_add_u32_e32 v53, 0x400, v52
	global_load_dwordx4 v[68:71], v53, s[24:25]
	v_add_u32_e32 v53, 0x800, v52
	global_load_dwordx4 v[72:75], v53, s[24:25]
	v_add_u32_e32 v53, 0xc00, v52
	global_load_dwordx4 v[76:79], v53, s[24:25]
	v_add_u32_e32 v53, 0x1000, v52
	global_load_dwordx4 v[80:83], v53, s[24:25]
	v_add_u32_e32 v53, 0x1400, v52
	global_load_dwordx4 v[84:87], v53, s[24:25]
	v_add_u32_e32 v53, 0x1800, v52
	global_load_dwordx4 v[88:91], v53, s[24:25]
	v_add_u32_e32 v53, 0x1c00, v52
	global_load_dwordx4 v[92:95], v53, s[24:25]
	v_add_u32_e32 v53, 0x2000, v52
	global_load_dwordx4 v[96:99], v53, s[24:25]
	v_add_u32_e32 v53, 0x2400, v52
	global_load_dwordx4 v[100:103], v53, s[24:25]
	v_add_u32_e32 v53, 0x2800, v52
	global_load_dwordx4 v[104:107], v53, s[24:25]
	s_and_b32 s26, s88, 7
	s_lshl_b32 s26, s26, 5
	s_bfe_u32 s31, s88, 0x30003
	s_sub_u32 s31, 7, s31
	s_add_u32 s26, s26, s31
	s_mov_b32 s41, 0
; __device__ __forceinline__ unsigned pk2(float lo, float hi) { unsigned r; asm("v_cvt_pk_bf16_f32 %0, %1, %2" : "=v"(r) : "v"(lo), "v"(hi)); return r; }
; __device__ __forceinline__ void ffn_fixup(const Args& a, int L, int panel) {
;     ...
;     for (int i = tid0; i < 8 * FF; i += 512) {
;         const int e = i / FF, c = i % FF, gi = 4 * panel + (e >> 1), side = e & 1;
;         const int row = 64 * gi + (side ? 63 : 0);
;         const size_t eo = ((size_t)gi * 2 + side) * FF + c;
;         float nb = 0.f, w;
;         if (side == 0) { w = cw[c]; if ((row & 2047) != 0) nb = EG[((size_t)(gi - 1) * 2 + 1) * FF + c]; }
;         else { w = cw[2 * FF + c]; if ((row & 2047) != 2047) nb = EG[((size_t)(gi + 1) * 2) * FF + c]; }
;         const float pre = EP[eo] + w * nb;
;         const float act = gelu_tanh(pre) * EU[eo];
;         ACT[(size_t)row * FF + c] = (bf16_t)(pk2(act, 0.f) & 0xffffu);
;     }
.Lfx_panel:
	s_lshl_b32 s27, s26, 2
	s_add_u32 s27, s27, s42
	s_lshl_b32 s28, s27, 1
	s_add_u32 s28, s28, s46
	s_mul_i32 s28, s28, 0x2c00
	s_lshl_b32 s29, s27, 6
	s_mul_i32 s31, s46, 63
	s_add_u32 s29, s29, s31
	s_mul_i32 s29, s29, 0x1600
	s_lshl_b32 s30, s27, 1
	s_cmp_eq_u32 s46, 0
	s_cbranch_scc0 .Lfx_s1
	s_sub_u32 s30, s30, 1
	s_and_b32 s31, s27, 31
	s_cmp_lg_u32 s31, 0
	s_branch .Lfx_sd
.Lfx_s1:
	s_add_u32 s30, s30, 2
	s_and_b32 s31, s27, 31
	s_cmp_lg_u32 s31, 31
.Lfx_sd:
	s_cselect_b32 s31, 1, 0
	s_mul_i32 s30, s30, 0x2c00
	v_add_u32_e32 v54, s28, v50
	v_add_u32_e32 v55, s30, v50
	v_add_u32_e32 v56, s29, v51
	v_add_u32_e32 v53, 0x0, v54
	global_load_dwordx4 v[0:3], v53, s[0:1]
	global_load_dwordx4 v[24:27], v53, s[6:7]
	v_add_u32_e32 v53, 0x400, v54
	global_load_dwordx4 v[4:7], v53, s[0:1]
	global_load_dwordx4 v[28:31], v53, s[6:7]
	v_add_u32_e32 v53, 0x800, v54
	global_load_dwordx4 v[8:11], v53, s[0:1]
	global_load_dwordx4 v[32:35], v53, s[6:7]
	v_add_u32_e32 v53, 0xc00, v54
	global_load_dwordx4 v[12:15], v53, s[0:1]
	global_load_dwordx4 v[36:39], v53, s[6:7]
	v_add_u32_e32 v53, 0x1000, v54
	global_load_dwordx4 v[16:19], v53, s[0:1]
	global_load_dwordx4 v[40:43], v53, s[6:7]
	v_add_u32_e32 v53, 0x1400, v54
	global_load_dwordx4 v[20:23], v53, s[0:1]
	global_load_dwordx4 v[44:47], v53, s[6:7]
	s_cmp_eq_u32 s31, 0
	s_cbranch_scc1 .Lfx_nonb0
	v_add_u32_e32 v53, 0x0, v55
	global_load_dwordx4 v[108:111], v53, s[4:5]
	v_add_u32_e32 v53, 0x400, v55
	global_load_dwordx4 v[112:115], v53, s[4:5]
	v_add_u32_e32 v53, 0x800, v55
	global_load_dwordx4 v[116:119], v53, s[4:5]
	v_add_u32_e32 v53, 0xc00, v55
	global_load_dwordx4 v[120:123], v53, s[4:5]
	v_add_u32_e32 v53, 0x1000, v55
	global_load_dwordx4 v[124:127], v53, s[4:5]
	v_add_u32_e32 v53, 0x1400, v55
	global_load_dwordx4 v[128:131], v53, s[4:5]
	s_branch .Lfx_nbd0
.Lfx_nonb0:
	v_mov_b32_e32 v108, 0
	v_mov_b32_e32 v109, 0
	v_mov_b32_e32 v110, 0
	v_mov_b32_e32 v111, 0
	v_mov_b32_e32 v112, 0
	v_mov_b32_e32 v113, 0
	v_mov_b32_e32 v114, 0
	v_mov_b32_e32 v115, 0
	v_mov_b32_e32 v116, 0
	v_mov_b32_e32 v117, 0
	v_mov_b32_e32 v118, 0
	v_mov_b32_e32 v119, 0
	v_mov_b32_e32 v120, 0
	v_mov_b32_e32 v121, 0
	v_mov_b32_e32 v122, 0
	v_mov_b32_e32 v123, 0
	v_mov_b32_e32 v124, 0
	v_mov_b32_e32 v125, 0
	v_mov_b32_e32 v126, 0
	v_mov_b32_e32 v127, 0
	v_mov_b32_e32 v128, 0
	v_mov_b32_e32 v129, 0
	v_mov_b32_e32 v130, 0
	v_mov_b32_e32 v131, 0
.Lfx_nbd0:
	s_waitcnt vmcnt(0)
	v_fmac_f32_e32 v0, v64, v108
	v_fmac_f32_e32 v1, v65, v109
	v_fmac_f32_e32 v2, v66, v110
	v_fmac_f32_e32 v3, v67, v111
	v_mul_f32_e32 v57, 0x3d372713, v0
	v_mul_f32_e32 v58, 0x3d372713, v1
	v_mul_f32_e32 v59, 0x3d372713, v2
	v_mul_f32_e32 v60, 0x3d372713, v3
	v_fma_f32 v57, v0, v57, 1.0
	v_fma_f32 v58, v1, v58, 1.0
	v_fma_f32 v59, v2, v59, 1.0
	v_fma_f32 v60, v3, v60, 1.0
	v_mul_f32_e32 v57, v0, v57
	v_mul_f32_e32 v58, v1, v58
	v_mul_f32_e32 v59, v2, v59
	v_mul_f32_e32 v60, v3, v60
	v_mul_f32_e32 v57, 0xc0135761, v57
	v_mul_f32_e32 v58, 0xc0135761, v58
	v_mul_f32_e32 v59, 0xc0135761, v59
	v_mul_f32_e32 v60, 0xc0135761, v60
	v_exp_f32_e32 v57, v57
	v_exp_f32_e32 v58, v58
	v_exp_f32_e32 v59, v59
	v_exp_f32_e32 v60, v60
	v_add_f32_e32 v57, 1.0, v57
	v_add_f32_e32 v58, 1.0, v58
	v_add_f32_e32 v59, 1.0, v59
	v_add_f32_e32 v60, 1.0, v60
	v_rcp_f32_e32 v57, v57
	v_rcp_f32_e32 v58, v58
	v_rcp_f32_e32 v59, v59
	v_rcp_f32_e32 v60, v60
	v_mul_f32_e32 v57, v0, v57
	v_mul_f32_e32 v58, v1, v58
	v_mul_f32_e32 v59, v2, v59
	v_mul_f32_e32 v60, v3, v60
	v_mul_f32_e32 v24, v24, v57
	v_mul_f32_e32 v25, v25, v58
	v_mul_f32_e32 v26, v26, v59
	v_mul_f32_e32 v27, v27, v60
	v_cvt_pk_bf16_f32 v24, v24, v25
	v_cvt_pk_bf16_f32 v25, v26, v27
	v_add_u32_e32 v53, 0x0, v56
	global_store_dwordx2 v53, v[24:25], s[12:13]
	v_fmac_f32_e32 v4, v68, v112
	v_fmac_f32_e32 v5, v69, v113
	v_fmac_f32_e32 v6, v70, v114
	v_fmac_f32_e32 v7, v71, v115
	v_mul_f32_e32 v57, 0x3d372713, v4
	v_mul_f32_e32 v58, 0x3d372713, v5
	v_mul_f32_e32 v59, 0x3d372713, v6
	v_mul_f32_e32 v60, 0x3d372713, v7
	v_fma_f32 v57, v4, v57, 1.0
	v_fma_f32 v58, v5, v58, 1.0
	v_fma_f32 v59, v6, v59, 1.0
	v_fma_f32 v60, v7, v60, 1.0
	v_mul_f32_e32 v57, v4, v57
	v_mul_f32_e32 v58, v5, v58
	v_mul_f32_e32 v59, v6, v59
	v_mul_f32_e32 v60, v7, v60
	v_mul_f32_e32 v57, 0xc0135761, v57
	v_mul_f32_e32 v58, 0xc0135761, v58
	v_mul_f32_e32 v59, 0xc0135761, v59
	v_mul_f32_e32 v60, 0xc0135761, v60
	v_exp_f32_e32 v57, v57
	v_exp_f32_e32 v58, v58
	v_exp_f32_e32 v59, v59
	v_exp_f32_e32 v60, v60
	v_add_f32_e32 v57, 1.0, v57
	v_add_f32_e32 v58, 1.0, v58
	v_add_f32_e32 v59, 1.0, v59
	v_add_f32_e32 v60, 1.0, v60
	v_rcp_f32_e32 v57, v57
	v_rcp_f32_e32 v58, v58
	v_rcp_f32_e32 v59, v59
	v_rcp_f32_e32 v60, v60
	v_mul_f32_e32 v57, v4, v57
	v_mul_f32_e32 v58, v5, v58
	v_mul_f32_e32 v59, v6, v59
	v_mul_f32_e32 v60, v7, v60
	v_mul_f32_e32 v28, v28, v57
	v_mul_f32_e32 v29, v29, v58
	v_mul_f32_e32 v30, v30, v59
	v_mul_f32_e32 v31, v31, v60
	v_cvt_pk_bf16_f32 v28, v28, v29
	v_cvt_pk_bf16_f32 v29, v30, v31
	v_add_u32_e32 v53, 0x200, v56
	global_store_dwordx2 v53, v[28:29], s[12:13]
	v_fmac_f32_e32 v8, v72, v116
	v_fmac_f32_e32 v9, v73, v117
	v_fmac_f32_e32 v10, v74, v118
	v_fmac_f32_e32 v11, v75, v119
	v_mul_f32_e32 v57, 0x3d372713, v8
	v_mul_f32_e32 v58, 0x3d372713, v9
	v_mul_f32_e32 v59, 0x3d372713, v10
	v_mul_f32_e32 v60, 0x3d372713, v11
	v_fma_f32 v57, v8, v57, 1.0
	v_fma_f32 v58, v9, v58, 1.0
	v_fma_f32 v59, v10, v59, 1.0
	v_fma_f32 v60, v11, v60, 1.0
	v_mul_f32_e32 v57, v8, v57
	v_mul_f32_e32 v58, v9, v58
	v_mul_f32_e32 v59, v10, v59
	v_mul_f32_e32 v60, v11, v60
	v_mul_f32_e32 v57, 0xc0135761, v57
	v_mul_f32_e32 v58, 0xc0135761, v58
; __device__ __forceinline__ unsigned pk2(float lo, float hi) { unsigned r; asm("v_cvt_pk_bf16_f32 %0, %1, %2" : "=v"(r) : "v"(lo), "v"(hi)); return r; }
; __device__ __forceinline__ void ffn_fixup(const Args& a, int L, int panel) {
;     ...
;     for (int i = tid0; i < 8 * FF; i += 512) {
;         const int e = i / FF, c = i % FF, gi = 4 * panel + (e >> 1), side = e & 1;
;         const int row = 64 * gi + (side ? 63 : 0);
;         const size_t eo = ((size_t)gi * 2 + side) * FF + c;
;         float nb = 0.f, w;
;         if (side == 0) { w = cw[c]; if ((row & 2047) != 0) nb = EG[((size_t)(gi - 1) * 2 + 1) * FF + c]; }
;         else { w = cw[2 * FF + c]; if ((row & 2047) != 2047) nb = EG[((size_t)(gi + 1) * 2) * FF + c]; }
;         const float pre = EP[eo] + w * nb;
;         const float act = gelu_tanh(pre) * EU[eo];
;         ACT[(size_t)row * FF + c] = (bf16_t)(pk2(act, 0.f) & 0xffffu);
;     }
	v_mul_f32_e32 v59, 0xc0135761, v59
	v_mul_f32_e32 v60, 0xc0135761, v60
	v_exp_f32_e32 v57, v57
	v_exp_f32_e32 v58, v58
	v_exp_f32_e32 v59, v59
	v_exp_f32_e32 v60, v60
	v_add_f32_e32 v57, 1.0, v57
	v_add_f32_e32 v58, 1.0, v58
	v_add_f32_e32 v59, 1.0, v59
	v_add_f32_e32 v60, 1.0, v60
	v_rcp_f32_e32 v57, v57
	v_rcp_f32_e32 v58, v58
	v_rcp_f32_e32 v59, v59
	v_rcp_f32_e32 v60, v60
	v_mul_f32_e32 v57, v8, v57
	v_mul_f32_e32 v58, v9, v58
	v_mul_f32_e32 v59, v10, v59
	v_mul_f32_e32 v60, v11, v60
	v_mul_f32_e32 v32, v32, v57
	v_mul_f32_e32 v33, v33, v58
	v_mul_f32_e32 v34, v34, v59
	v_mul_f32_e32 v35, v35, v60
	v_cvt_pk_bf16_f32 v32, v32, v33
	v_cvt_pk_bf16_f32 v33, v34, v35
	v_add_u32_e32 v53, 0x400, v56
	global_store_dwordx2 v53, v[32:33], s[12:13]
	v_fmac_f32_e32 v12, v76, v120
	v_fmac_f32_e32 v13, v77, v121
	v_fmac_f32_e32 v14, v78, v122
	v_fmac_f32_e32 v15, v79, v123
	v_mul_f32_e32 v57, 0x3d372713, v12
	v_mul_f32_e32 v58, 0x3d372713, v13
	v_mul_f32_e32 v59, 0x3d372713, v14
	v_mul_f32_e32 v60, 0x3d372713, v15
	v_fma_f32 v57, v12, v57, 1.0
	v_fma_f32 v58, v13, v58, 1.0
	v_fma_f32 v59, v14, v59, 1.0
	v_fma_f32 v60, v15, v60, 1.0
	v_mul_f32_e32 v57, v12, v57
	v_mul_f32_e32 v58, v13, v58
	v_mul_f32_e32 v59, v14, v59
	v_mul_f32_e32 v60, v15, v60
	v_mul_f32_e32 v57, 0xc0135761, v57
	v_mul_f32_e32 v58, 0xc0135761, v58
	v_mul_f32_e32 v59, 0xc0135761, v59
	v_mul_f32_e32 v60, 0xc0135761, v60
	v_exp_f32_e32 v57, v57
	v_exp_f32_e32 v58, v58
	v_exp_f32_e32 v59, v59
	v_exp_f32_e32 v60, v60
	v_add_f32_e32 v57, 1.0, v57
	v_add_f32_e32 v58, 1.0, v58
	v_add_f32_e32 v59, 1.0, v59
	v_add_f32_e32 v60, 1.0, v60
	v_rcp_f32_e32 v57, v57
	v_rcp_f32_e32 v58, v58
	v_rcp_f32_e32 v59, v59
	v_rcp_f32_e32 v60, v60
	v_mul_f32_e32 v57, v12, v57
	v_mul_f32_e32 v58, v13, v58
	v_mul_f32_e32 v59, v14, v59
	v_mul_f32_e32 v60, v15, v60
	v_mul_f32_e32 v36, v36, v57
	v_mul_f32_e32 v37, v37, v58
	v_mul_f32_e32 v38, v38, v59
	v_mul_f32_e32 v39, v39, v60
	v_cvt_pk_bf16_f32 v36, v36, v37
	v_cvt_pk_bf16_f32 v37, v38, v39
	v_add_u32_e32 v53, 0x600, v56
	global_store_dwordx2 v53, v[36:37], s[12:13]
	v_fmac_f32_e32 v16, v80, v124
	v_fmac_f32_e32 v17, v81, v125
	v_fmac_f32_e32 v18, v82, v126
	v_fmac_f32_e32 v19, v83, v127
	v_mul_f32_e32 v57, 0x3d372713, v16
	v_mul_f32_e32 v58, 0x3d372713, v17
	v_mul_f32_e32 v59, 0x3d372713, v18
	v_mul_f32_e32 v60, 0x3d372713, v19
	v_fma_f32 v57, v16, v57, 1.0
	v_fma_f32 v58, v17, v58, 1.0
	v_fma_f32 v59, v18, v59, 1.0
	v_fma_f32 v60, v19, v60, 1.0
	v_mul_f32_e32 v57, v16, v57
	v_mul_f32_e32 v58, v17, v58
	v_mul_f32_e32 v59, v18, v59
	v_mul_f32_e32 v60, v19, v60
	v_mul_f32_e32 v57, 0xc0135761, v57
	v_mul_f32_e32 v58, 0xc0135761, v58
	v_mul_f32_e32 v59, 0xc0135761, v59
	v_mul_f32_e32 v60, 0xc0135761, v60
	v_exp_f32_e32 v57, v57
	v_exp_f32_e32 v58, v58
	v_exp_f32_e32 v59, v59
	v_exp_f32_e32 v60, v60
	v_add_f32_e32 v57, 1.0, v57
	v_add_f32_e32 v58, 1.0, v58
	v_add_f32_e32 v59, 1.0, v59
	v_add_f32_e32 v60, 1.0, v60
	v_rcp_f32_e32 v57, v57
	v_rcp_f32_e32 v58, v58
	v_rcp_f32_e32 v59, v59
	v_rcp_f32_e32 v60, v60
	v_mul_f32_e32 v57, v16, v57
	v_mul_f32_e32 v58, v17, v58
	v_mul_f32_e32 v59, v18, v59
	v_mul_f32_e32 v60, v19, v60
	v_mul_f32_e32 v40, v40, v57
	v_mul_f32_e32 v41, v41, v58
	v_mul_f32_e32 v42, v42, v59
	v_mul_f32_e32 v43, v43, v60
	v_cvt_pk_bf16_f32 v40, v40, v41
	v_cvt_pk_bf16_f32 v41, v42, v43
	v_add_u32_e32 v53, 0x800, v56
	global_store_dwordx2 v53, v[40:41], s[12:13]
	v_fmac_f32_e32 v20, v84, v128
	v_fmac_f32_e32 v21, v85, v129
	v_fmac_f32_e32 v22, v86, v130
	v_fmac_f32_e32 v23, v87, v131
	v_mul_f32_e32 v57, 0x3d372713, v20
	v_mul_f32_e32 v58, 0x3d372713, v21
	v_mul_f32_e32 v59, 0x3d372713, v22
	v_mul_f32_e32 v60, 0x3d372713, v23
	v_fma_f32 v57, v20, v57, 1.0
	v_fma_f32 v58, v21, v58, 1.0
	v_fma_f32 v59, v22, v59, 1.0
	v_fma_f32 v60, v23, v60, 1.0
	v_mul_f32_e32 v57, v20, v57
	v_mul_f32_e32 v58, v21, v58
	v_mul_f32_e32 v59, v22, v59
	v_mul_f32_e32 v60, v23, v60
	v_mul_f32_e32 v57, 0xc0135761, v57
	v_mul_f32_e32 v58, 0xc0135761, v58
	v_mul_f32_e32 v59, 0xc0135761, v59
	v_mul_f32_e32 v60, 0xc0135761, v60
	v_exp_f32_e32 v57, v57
	v_exp_f32_e32 v58, v58
	v_exp_f32_e32 v59, v59
	v_exp_f32_e32 v60, v60
	v_add_f32_e32 v57, 1.0, v57
	v_add_f32_e32 v58, 1.0, v58
	v_add_f32_e32 v59, 1.0, v59
	v_add_f32_e32 v60, 1.0, v60
	v_rcp_f32_e32 v57, v57
	v_rcp_f32_e32 v58, v58
	v_rcp_f32_e32 v59, v59
	v_rcp_f32_e32 v60, v60
	v_mul_f32_e32 v57, v20, v57
	v_mul_f32_e32 v58, v21, v58
	v_mul_f32_e32 v59, v22, v59
	v_mul_f32_e32 v60, v23, v60
	v_mul_f32_e32 v44, v44, v57
	v_mul_f32_e32 v45, v45, v58
	v_mul_f32_e32 v46, v46, v59
	v_mul_f32_e32 v47, v47, v60
	v_cvt_pk_bf16_f32 v44, v44, v45
	v_cvt_pk_bf16_f32 v45, v46, v47
	v_add_u32_e32 v53, 0xa00, v56
	global_store_dwordx2 v53, v[44:45], s[12:13]
	v_add_u32_e32 v53, 0x1800, v54
	global_load_dwordx4 v[0:3], v53, s[0:1]
	global_load_dwordx4 v[24:27], v53, s[6:7]
	v_add_u32_e32 v53, 0x1c00, v54
	global_load_dwordx4 v[4:7], v53, s[0:1]
	global_load_dwordx4 v[28:31], v53, s[6:7]
	v_add_u32_e32 v53, 0x2000, v54
	global_load_dwordx4 v[8:11], v53, s[0:1]
	global_load_dwordx4 v[32:35], v53, s[6:7]
	v_add_u32_e32 v53, 0x2400, v54
	global_load_dwordx4 v[12:15], v53, s[0:1]
	global_load_dwordx4 v[36:39], v53, s[6:7]
	v_add_u32_e32 v53, 0x2800, v54
	global_load_dwordx4 v[16:19], v53, s[0:1]
	global_load_dwordx4 v[40:43], v53, s[6:7]
	s_cmp_eq_u32 s31, 0
	s_cbranch_scc1 .Lfx_nonb6
	v_add_u32_e32 v53, 0x1800, v55
	global_load_dwordx4 v[108:111], v53, s[4:5]
	v_add_u32_e32 v53, 0x1c00, v55
	global_load_dwordx4 v[112:115], v53, s[4:5]
	v_add_u32_e32 v53, 0x2000, v55
	global_load_dwordx4 v[116:119], v53, s[4:5]
	v_add_u32_e32 v53, 0x2400, v55
	global_load_dwordx4 v[120:123], v53, s[4:5]
	v_add_u32_e32 v53, 0x2800, v55
	global_load_dwordx4 v[124:127], v53, s[4:5]
	s_branch .Lfx_nbd6
; __device__ __forceinline__ void ffn_fixup(const Args& a, int L, int panel) {
;     ...
;         if (side == 0) { w = cw[c]; if ((row & 2047) != 0) nb = EG[((size_t)(gi - 1) * 2 + 1) * FF + c]; }
;         else { w = cw[2 * FF + c]; if ((row & 2047) != 2047) nb = EG[((size_t)(gi + 1) * 2) * FF + c]; }
.Lfx_nonb6:
	v_mov_b32_e32 v108, 0
	v_mov_b32_e32 v109, 0
	v_mov_b32_e32 v110, 0
	v_mov_b32_e32 v111, 0
	v_mov_b32_e32 v112, 0
	v_mov_b32_e32 v113, 0
	v_mov_b32_e32 v114, 0
	v_mov_b32_e32 v115, 0
	v_mov_b32_e32 v116, 0
	v_mov_b32_e32 v117, 0
	v_mov_b32_e32 v118, 0
	v_mov_b32_e32 v119, 0
	v_mov_b32_e32 v120, 0
	v_mov_b32_e32 v121, 0
	v_mov_b32_e32 v122, 0
	v_mov_b32_e32 v123, 0
	v_mov_b32_e32 v124, 0
	v_mov_b32_e32 v125, 0
	v_mov_b32_e32 v126, 0
	v_mov_b32_e32 v127, 0
; __device__ __forceinline__ unsigned pk2(float lo, float hi) { unsigned r; asm("v_cvt_pk_bf16_f32 %0, %1, %2" : "=v"(r) : "v"(lo), "v"(hi)); return r; }
;     __device__ __forceinline__ bool next(int i, Unit& u) const { if (i >= 4) return false; u.pm = pm; u.pn = i; return true; }
; __device__ __forceinline__ void ffn_fixup(const Args& a, int L, int panel) {
;     ...
;     for (int i = tid0; i < 8 * FF; i += 512) {
;         const int e = i / FF, c = i % FF, gi = 4 * panel + (e >> 1), side = e & 1;
;         const int row = 64 * gi + (side ? 63 : 0);
;         const size_t eo = ((size_t)gi * 2 + side) * FF + c;
;         float nb = 0.f, w;
;         if (side == 0) { w = cw[c]; if ((row & 2047) != 0) nb = EG[((size_t)(gi - 1) * 2 + 1) * FF + c]; }
;         else { w = cw[2 * FF + c]; if ((row & 2047) != 2047) nb = EG[((size_t)(gi + 1) * 2) * FF + c]; }
;         const float pre = EP[eo] + w * nb;
;         const float act = gelu_tanh(pre) * EU[eo];
;         ACT[(size_t)row * FF + c] = (bf16_t)(pk2(act, 0.f) & 0xffffu);
;     }
; __device__ __forceinline__ void run_phase(const Args& a0, int ph, LAS unsigned char* lds) {
;     ...
;         { Unit u; int last = -1; for (int i = 0; S.next(i, u); ++i) if (u.pm != last) { ffn_fixup(a, L, u.pm); last = u.pm; } }
;         __syncthreads();
.Lfx_nbd6:
	s_waitcnt vmcnt(0)
	v_fmac_f32_e32 v0, v88, v108
	v_fmac_f32_e32 v1, v89, v109
	v_fmac_f32_e32 v2, v90, v110
	v_fmac_f32_e32 v3, v91, v111
	v_mul_f32_e32 v57, 0x3d372713, v0
	v_mul_f32_e32 v58, 0x3d372713, v1
	v_mul_f32_e32 v59, 0x3d372713, v2
	v_mul_f32_e32 v60, 0x3d372713, v3
	v_fma_f32 v57, v0, v57, 1.0
	v_fma_f32 v58, v1, v58, 1.0
	v_fma_f32 v59, v2, v59, 1.0
	v_fma_f32 v60, v3, v60, 1.0
	v_mul_f32_e32 v57, v0, v57
	v_mul_f32_e32 v58, v1, v58
	v_mul_f32_e32 v59, v2, v59
	v_mul_f32_e32 v60, v3, v60
	v_mul_f32_e32 v57, 0xc0135761, v57
	v_mul_f32_e32 v58, 0xc0135761, v58
	v_mul_f32_e32 v59, 0xc0135761, v59
	v_mul_f32_e32 v60, 0xc0135761, v60
	v_exp_f32_e32 v57, v57
	v_exp_f32_e32 v58, v58
	v_exp_f32_e32 v59, v59
	v_exp_f32_e32 v60, v60
	v_add_f32_e32 v57, 1.0, v57
	v_add_f32_e32 v58, 1.0, v58
	v_add_f32_e32 v59, 1.0, v59
	v_add_f32_e32 v60, 1.0, v60
	v_rcp_f32_e32 v57, v57
	v_rcp_f32_e32 v58, v58
	v_rcp_f32_e32 v59, v59
	v_rcp_f32_e32 v60, v60
	v_mul_f32_e32 v57, v0, v57
	v_mul_f32_e32 v58, v1, v58
	v_mul_f32_e32 v59, v2, v59
	v_mul_f32_e32 v60, v3, v60
	v_mul_f32_e32 v24, v24, v57
	v_mul_f32_e32 v25, v25, v58
	v_mul_f32_e32 v26, v26, v59
	v_mul_f32_e32 v27, v27, v60
	v_cvt_pk_bf16_f32 v24, v24, v25
	v_cvt_pk_bf16_f32 v25, v26, v27
	v_add_u32_e32 v53, 0xc00, v56
	global_store_dwordx2 v53, v[24:25], s[12:13]
	v_fmac_f32_e32 v4, v92, v112
	v_fmac_f32_e32 v5, v93, v113
	v_fmac_f32_e32 v6, v94, v114
	v_fmac_f32_e32 v7, v95, v115
	v_mul_f32_e32 v57, 0x3d372713, v4
	v_mul_f32_e32 v58, 0x3d372713, v5
	v_mul_f32_e32 v59, 0x3d372713, v6
	v_mul_f32_e32 v60, 0x3d372713, v7
	v_fma_f32 v57, v4, v57, 1.0
	v_fma_f32 v58, v5, v58, 1.0
	v_fma_f32 v59, v6, v59, 1.0
	v_fma_f32 v60, v7, v60, 1.0
	v_mul_f32_e32 v57, v4, v57
	v_mul_f32_e32 v58, v5, v58
	v_mul_f32_e32 v59, v6, v59
	v_mul_f32_e32 v60, v7, v60
	v_mul_f32_e32 v57, 0xc0135761, v57
	v_mul_f32_e32 v58, 0xc0135761, v58
	v_mul_f32_e32 v59, 0xc0135761, v59
	v_mul_f32_e32 v60, 0xc0135761, v60
	v_exp_f32_e32 v57, v57
	v_exp_f32_e32 v58, v58
	v_exp_f32_e32 v59, v59
	v_exp_f32_e32 v60, v60
	v_add_f32_e32 v57, 1.0, v57
	v_add_f32_e32 v58, 1.0, v58
	v_add_f32_e32 v59, 1.0, v59
	v_add_f32_e32 v60, 1.0, v60
	v_rcp_f32_e32 v57, v57
	v_rcp_f32_e32 v58, v58
	v_rcp_f32_e32 v59, v59
	v_rcp_f32_e32 v60, v60
	v_mul_f32_e32 v57, v4, v57
	v_mul_f32_e32 v58, v5, v58
	v_mul_f32_e32 v59, v6, v59
	v_mul_f32_e32 v60, v7, v60
	v_mul_f32_e32 v28, v28, v57
	v_mul_f32_e32 v29, v29, v58
	v_mul_f32_e32 v30, v30, v59
	v_mul_f32_e32 v31, v31, v60
	v_cvt_pk_bf16_f32 v28, v28, v29
	v_cvt_pk_bf16_f32 v29, v30, v31
	v_add_u32_e32 v53, 0xe00, v56
	global_store_dwordx2 v53, v[28:29], s[12:13]
	v_fmac_f32_e32 v8, v96, v116
	v_fmac_f32_e32 v9, v97, v117
	v_fmac_f32_e32 v10, v98, v118
	v_fmac_f32_e32 v11, v99, v119
	v_mul_f32_e32 v57, 0x3d372713, v8
	v_mul_f32_e32 v58, 0x3d372713, v9
	v_mul_f32_e32 v59, 0x3d372713, v10
	v_mul_f32_e32 v60, 0x3d372713, v11
	v_fma_f32 v57, v8, v57, 1.0
	v_fma_f32 v58, v9, v58, 1.0
	v_fma_f32 v59, v10, v59, 1.0
	v_fma_f32 v60, v11, v60, 1.0
	v_mul_f32_e32 v57, v8, v57
	v_mul_f32_e32 v58, v9, v58
	v_mul_f32_e32 v59, v10, v59
	v_mul_f32_e32 v60, v11, v60
	v_mul_f32_e32 v57, 0xc0135761, v57
	v_mul_f32_e32 v58, 0xc0135761, v58
	v_mul_f32_e32 v59, 0xc0135761, v59
	v_mul_f32_e32 v60, 0xc0135761, v60
	v_exp_f32_e32 v57, v57
	v_exp_f32_e32 v58, v58
	v_exp_f32_e32 v59, v59
	v_exp_f32_e32 v60, v60
	v_add_f32_e32 v57, 1.0, v57
	v_add_f32_e32 v58, 1.0, v58
	v_add_f32_e32 v59, 1.0, v59
	v_add_f32_e32 v60, 1.0, v60
	v_rcp_f32_e32 v57, v57
	v_rcp_f32_e32 v58, v58
	v_rcp_f32_e32 v59, v59
	v_rcp_f32_e32 v60, v60
	v_mul_f32_e32 v57, v8, v57
	v_mul_f32_e32 v58, v9, v58
	v_mul_f32_e32 v59, v10, v59
	v_mul_f32_e32 v60, v11, v60
	v_mul_f32_e32 v32, v32, v57
	v_mul_f32_e32 v33, v33, v58
	v_mul_f32_e32 v34, v34, v59
	v_mul_f32_e32 v35, v35, v60
	v_cvt_pk_bf16_f32 v32, v32, v33
	v_cvt_pk_bf16_f32 v33, v34, v35
	v_add_u32_e32 v53, 0x1000, v56
	global_store_dwordx2 v53, v[32:33], s[12:13]
	v_fmac_f32_e32 v12, v100, v120
	v_fmac_f32_e32 v13, v101, v121
	v_fmac_f32_e32 v14, v102, v122
	v_fmac_f32_e32 v15, v103, v123
	v_mul_f32_e32 v57, 0x3d372713, v12
	v_mul_f32_e32 v58, 0x3d372713, v13
	v_mul_f32_e32 v59, 0x3d372713, v14
	v_mul_f32_e32 v60, 0x3d372713, v15
	v_fma_f32 v57, v12, v57, 1.0
	v_fma_f32 v58, v13, v58, 1.0
	v_fma_f32 v59, v14, v59, 1.0
	v_fma_f32 v60, v15, v60, 1.0
	v_mul_f32_e32 v57, v12, v57
	v_mul_f32_e32 v58, v13, v58
	v_mul_f32_e32 v59, v14, v59
	v_mul_f32_e32 v60, v15, v60
	v_mul_f32_e32 v57, 0xc0135761, v57
	v_mul_f32_e32 v58, 0xc0135761, v58
	v_mul_f32_e32 v59, 0xc0135761, v59
	v_mul_f32_e32 v60, 0xc0135761, v60
	v_exp_f32_e32 v57, v57
	v_exp_f32_e32 v58, v58
	v_exp_f32_e32 v59, v59
	v_exp_f32_e32 v60, v60
	v_add_f32_e32 v57, 1.0, v57
	v_add_f32_e32 v58, 1.0, v58
	v_add_f32_e32 v59, 1.0, v59
	v_add_f32_e32 v60, 1.0, v60
	v_rcp_f32_e32 v57, v57
	v_rcp_f32_e32 v58, v58
	v_rcp_f32_e32 v59, v59
	v_rcp_f32_e32 v60, v60
	v_mul_f32_e32 v57, v12, v57
	v_mul_f32_e32 v58, v13, v58
	v_mul_f32_e32 v59, v14, v59
	v_mul_f32_e32 v60, v15, v60
	v_mul_f32_e32 v36, v36, v57
	v_mul_f32_e32 v37, v37, v58
	v_mul_f32_e32 v38, v38, v59
	v_mul_f32_e32 v39, v39, v60
	v_cvt_pk_bf16_f32 v36, v36, v37
	v_cvt_pk_bf16_f32 v37, v38, v39
	v_add_u32_e32 v53, 0x1200, v56
	global_store_dwordx2 v53, v[36:37], s[12:13]
	v_fmac_f32_e32 v16, v104, v124
	v_fmac_f32_e32 v17, v105, v125
	v_fmac_f32_e32 v18, v106, v126
	v_fmac_f32_e32 v19, v107, v127
	v_mul_f32_e32 v57, 0x3d372713, v16
	v_mul_f32_e32 v58, 0x3d372713, v17
	v_mul_f32_e32 v59, 0x3d372713, v18
	v_mul_f32_e32 v60, 0x3d372713, v19
	v_fma_f32 v57, v16, v57, 1.0
	v_fma_f32 v58, v17, v58, 1.0
	v_fma_f32 v59, v18, v59, 1.0
	v_fma_f32 v60, v19, v60, 1.0
	v_mul_f32_e32 v57, v16, v57
	v_mul_f32_e32 v58, v17, v58
	v_mul_f32_e32 v59, v18, v59
	v_mul_f32_e32 v60, v19, v60
	v_mul_f32_e32 v57, 0xc0135761, v57
	v_mul_f32_e32 v58, 0xc0135761, v58
	v_mul_f32_e32 v59, 0xc0135761, v59
	v_mul_f32_e32 v60, 0xc0135761, v60
	v_exp_f32_e32 v57, v57
	v_exp_f32_e32 v58, v58
	v_exp_f32_e32 v59, v59
	v_exp_f32_e32 v60, v60
	v_add_f32_e32 v57, 1.0, v57
	v_add_f32_e32 v58, 1.0, v58
	v_add_f32_e32 v59, 1.0, v59
	v_add_f32_e32 v60, 1.0, v60
	v_rcp_f32_e32 v57, v57
	v_rcp_f32_e32 v58, v58
	v_rcp_f32_e32 v59, v59
	v_rcp_f32_e32 v60, v60
	v_mul_f32_e32 v57, v16, v57
	v_mul_f32_e32 v58, v17, v58
	v_mul_f32_e32 v59, v18, v59
	v_mul_f32_e32 v60, v19, v60
	v_mul_f32_e32 v40, v40, v57
	v_mul_f32_e32 v41, v41, v58
	v_mul_f32_e32 v42, v42, v59
	v_mul_f32_e32 v43, v43, v60
	v_cvt_pk_bf16_f32 v40, v40, v41
	v_cvt_pk_bf16_f32 v41, v42, v43
	v_add_u32_e32 v53, 0x1400, v56
	global_store_dwordx2 v53, v[40:41], s[12:13]
	s_add_u32 s26, s26, 8
	s_add_u32 s41, s41, 1
	s_cmp_lt_u32 s41, 4
	s_cbranch_scc1 .Lfx_panel
	s_waitcnt vmcnt(0)
	s_mov_b64 s[28:29], -1
	s_add_u32 s26, s88, 0x400
	s_mov_b32 s27, 0
	s_movk_i32 s46, 0x7ff
	s_branch .LBB0_41
.Lfx_orig:
	s_mov_b32 s41, 0
	s_mov_b32 s30, -1
	s_movk_i32 s46, 0x7ff
	s_branch .LBB0_20

;     __device__ __forceinline__ bool next(int i, Unit& u) const { if (i >= 4) return false; u.pm = pm; u.pn = i; return true; }
;     __device__ __forceinline__ bool next(int i, Unit& u) const {
;         const long L = (long)i * G + c; if (L >= nwg) return false;
;         int wgid = (int)L; { const int q = nwg / NXCD, r = nwg % NXCD, xcd = wgid % NXCD, off = wgid / NXCD; wgid = (xcd < r ? xcd * (q + 1) : r * (q + 1) + (xcd - r) * q) + off; }
;         const int nig = WGM * nN, gid = wgid / nig, fm = gid * WGM, gsz = (nM - fm) < WGM ? (nM - fm) : WGM;
;         u.pm = fm + ((wgid % nig) % gsz); u.pn = (wgid % nig) / gsz; return true;
; __device__ __forceinline__ void run_phase(const Args& a0, int ph, LAS unsigned char* lds) {
;     ...
;         { Unit u; int last = -1; for (int i = 0; S.next(i, u); ++i) if (u.pm != last) { ffn_fixup(a, L, u.pm); last = u.pm; } }
.LBB0_25:
	s_ashr_i32 s26, s28, 3
	s_add_i32 s26, s31, s26
	s_xor_b32 s26, s26, 0x7f
	s_ashr_i32 s27, s26, 31
	s_lshr_b32 s27, s27, 27
	s_add_i32 s27, s26, s27
	s_ashr_i32 s28, s27, 5
	s_lshl_b32 s42, s28, 3
	s_sub_i32 s28, 0x100, s42
	s_min_i32 s28, s28, 8
	s_abs_i32 s28, s28
	v_cvt_f32_u32_e32 v0, s28
	s_sub_i32 s29, 0, s28
	s_andn2_b32 s27, s27, 31
	s_sub_i32 s26, s26, s27
	v_rcp_iflag_f32_e32 v0, v0
	s_ashr_i32 s27, s26, 31
	s_abs_i32 s26, s26
	v_mul_f32_e32 v0, 0x4f7ffffe, v0
	v_cvt_u32_f32_e32 v0, v0
	s_nop 0
	v_readfirstlane_b32 s31, v0
	s_mul_i32 s29, s29, s31
	s_mul_hi_u32 s29, s31, s29
	s_add_i32 s31, s31, s29
	s_mul_hi_u32 s29, s26, s31
	s_mul_i32 s29, s29, s28
	s_sub_i32 s26, s26, s29
	s_sub_i32 s29, s26, s28
	s_cmp_ge_u32 s26, s28
	s_cselect_b32 s26, s29, s26
	s_sub_i32 s29, s26, s28
	s_cmp_ge_u32 s26, s28
	s_cselect_b32 s26, s29, s26
	s_xor_b32 s26, s26, s27
	s_sub_i32 s26, s26, s27
	s_add_i32 s42, s42, s26
	s_cmp_lg_u32 s42, s30
	s_cbranch_scc0 .LBB0_18
	v_mov_b32_e32 v6, v225
	s_nop 0
	s_nop 0
	v_cmp_gt_i32_e32 vcc, s57, v6
	s_and_saveexec_b64 s[26:27], vcc
	s_cbranch_execz .LBB0_17
	s_lshl_b32 s43, s42, 2
	s_mov_b64 s[28:29], 0
	s_branch .LBB0_29

; __device__ __forceinline__ int tidx() { int t = threadIdx.x; asm volatile("" : "+v"(t)); return t; }
;     __device__ __forceinline__ bool next(int i, Unit& u) const { if (i >= 4) return false; u.pm = pm; u.pn = i; return true; }
; #define PG8_BAR __builtin_amdgcn_s_barrier()
;     __device__ __forceinline__ bool next(int i, Unit& u) const {
;         const long L = (long)i * G + c; if (L >= nwg) return false;
;         int wgid = (int)L; { const int q = nwg / NXCD, r = nwg % NXCD, xcd = wgid % NXCD, off = wgid / NXCD; wgid = (xcd < r ? xcd * (q + 1) : r * (q + 1) + (xcd - r) * q) + off; }
;         const int nig = WGM * nN, gid = wgid / nig, fm = gid * WGM, gsz = (nM - fm) < WGM ? (nM - fm) : WGM;
;         u.pm = fm + ((wgid % nig) % gsz); u.pn = (wgid % nig) / gsz; return true;
; template <class Epi, class Sched>
; __device__ __forceinline__ void gemm_phase(LAS unsigned char* lds, const Gemm g, const Sched& S, const Epi& E) {
;     const int tid = tidx(), wid = __builtin_amdgcn_readfirstlane(tid >> 6), lane = tid & 63, wr = wid >> 2, wc = wid & 3, fr = lane & 15, fq = lane >> 4;
;     const int K = g.K, nt = K / BK;
;     unsigned voffA[2], voffB[2];
; #pragma unroll
;     for (int i = 0; i < 2; ++i) { int R, C; stage_rc(tid * 16 + i * 8192, R, C); voffA[i] = (unsigned)(R * K + C) * 2u; voffB[i] = voffA[i]; }
;     const size_t kstep = (size_t)(BK * 2);
;     const size_t hstep = (size_t)HALF * K * 2;
;     const size_t tstep = 2 * hstep;
;     const unsigned ldsw = (unsigned)wid * 1024u;
;     const int aoff = lds_byte(wr * 64 + fr, fq * 8), boff = lds_byte(wc * 32 + fr, fq * 8);
;     ...
;     Unit cur, nxt; int ui = 0;
;     if (!S.next(0, cur)) return;
;     f32x4 acc[2][2][4][2];
; #pragma unroll
;     for (int a = 0; a < 2; ++a)
; #pragma unroll
;         for (int b = 0; b < 2; ++b)
; #pragma unroll
;             for (int m = 0; m < 4; ++m)
; #pragma unroll
;                 for (int n = 0; n < 2; ++n) acc[a][b][m][n] = (f32x4){0.f, 0.f, 0.f, 0.f};
;     bf16x8 At[4][2], B0[2][2], B1[2][2];
;     const char* cA = (const char*)g.A + (size_t)cur.pm * tstep; const char* cB = (const char*)g.Bt + (size_t)cur.pn * tstep;
;     PG8_STAGE(PG8_SB(0, 0), cB, voffB); PG8_STAGE(PG8_SA(0, 0), cA, voffA); PG8_STAGE(PG8_SB(0, 1), cB + hstep, voffB); PG8_STAGE(PG8_SA(0, 1), cA + hstep, voffA);
;     if (wr == 1) PG8_BAR;
;     PG8_WAIT_V(4); PG8_BAR;
.LBB0_46:
	v_bfe_i32 v2, v0, 27, 1
	v_lshlrev_b32_e32 v5, 4, v0
	v_lshrrev_b32_e32 v2, 22, v2
	v_add_u32_e32 v2, v5, v2
	v_and_b32_e32 v2, 0xfffffc00, v2
	v_ashrrev_i32_e32 v1, 31, v0
	v_sub_u32_e32 v2, v5, v2
	v_lshrrev_b32_e32 v1, 26, v1
	v_lshrrev_b32_e32 v3, 4, v2
	v_add_u32_e32 v1, v0, v1
	v_bitop3_b32 v4, v3, v2, 32 bitop3:0x6c
	v_ashrrev_i32_e32 v2, 31, v2
	v_readlane_b32 s0, v254, 59
	v_ashrrev_i32_e32 v1, 6, v1
	v_lshrrev_b32_e32 v2, 26, v2
	v_readlane_b32 s1, v254, 60
	s_mov_b32 s6, s0
	v_lshlrev_b32_e32 v3, 3, v1
	v_add_u32_e32 v2, v4, v2
	s_mul_i32 s1, s6, 0x580000
	v_and_b32_e32 v6, 0xfffff0, v3
	v_ashrrev_i32_e32 v3, 6, v2
	s_mul_hi_i32 s0, s0, 0x580000
	s_add_u32 s1, s80, s1
	v_mul_i32_i24_e32 v7, 64, v3
	s_addc_u32 s0, s81, s0
	v_add_u32_e32 v6, v3, v6
	v_lshlrev_b32_e32 v2, 5, v1
	v_sub_u32_e32 v4, v4, v7
	s_add_u32 s35, s1, 0x248a000
	v_and_b32_e32 v2, 32, v2
	v_ashrrev_i16_sdwa v4, v231, sext(v4) dst_sel:DWORD dst_unused:UNUSED_PAD src0_sel:DWORD src1_sel:BYTE_0
	v_mul_lo_u32 v6, v6, s61
	s_addc_u32 s36, s0, 0
	v_bfe_i32 v4, v4, 0, 16
	v_or_b32_e32 v6, v6, v2
	s_add_i32 s4, s4, s5
	s_xor_b32 s4, s4, 0x7f
	v_add_lshl_u32 v154, v6, v4, 1
	v_add_u32_e32 v6, 0x2000, v5
	s_ashr_i32 s5, s4, 31
	v_ashrrev_i32_e32 v5, 31, v6
	s_lshr_b32 s5, s5, 27
	v_lshrrev_b32_e32 v5, 22, v5
	s_add_i32 s5, s4, s5
	v_add_u32_e32 v5, v6, v5
	s_ashr_i32 s6, s5, 5
	s_and_b32 s5, s5, 0xffe0
	v_ashrrev_i32_e32 v5, 10, v5
	s_sub_i32 s5, s4, s5
	v_mul_i32_i24_e32 v7, 0x400, v5
	s_bfe_i32 s4, s5, 0x80000
	v_sub_u32_e32 v6, v6, v7
	s_bfe_u32 s4, s4, 0x3000c
	v_lshrrev_b32_e32 v7, 4, v6
	s_add_i32 s7, s5, s4
	v_bitop3_b32 v8, v7, v6, 32 bitop3:0x6c
	s_bfe_i32 s4, s7, 0x80000
	s_and_b32 s7, s7, 0xf8
	v_ashrrev_i32_e32 v7, 31, v8
	s_sext_i32_i16 s4, s4
	s_sub_i32 s5, s5, s7
	v_lshrrev_b32_e32 v7, 26, v7
	s_ashr_i32 s1, s34, 6
	s_lshl_b32 s6, s6, 3
	s_sext_i32_i8 s5, s5
	s_ashr_i32 s7, s4, 3
	s_ashr_i32 s0, s34, 8
	v_lshlrev_b32_e32 v6, 3, v5
	v_add_u32_e32 v9, v8, v7
	s_lshl_b32 s37, s1, 10
	s_add_i32 s50, s6, s5
	s_mul_hi_i32 s24, s7, 0x160000
	s_mul_i32 s7, s7, 0x160000
	v_and_b32_e32 v6, 0xfffff0, v6
	v_ashrrev_i32_e32 v7, 6, v9
	v_and_b32_e32 v9, 0xc0, v9
	s_add_u32 s26, s35, s7
	v_add_u32_e32 v10, v7, v6
	v_lshlrev_b32_e32 v6, 5, v5
	v_sub_u32_e32 v8, v8, v9
	s_addc_u32 s27, s36, s24
	s_add_i32 s38, s37, 0
	v_and_b32_e32 v6, 32, v6
	v_ashrrev_i16_sdwa v8, v231, sext(v8) dst_sel:DWORD dst_unused:UNUSED_PAD src0_sel:DWORD src1_sel:BYTE_0
	v_mul_lo_u32 v9, v10, s61
	s_add_i32 m0, s38, 0x10000
	v_bfe_i32 v8, v8, 0, 16
	v_or_b32_e32 v9, v9, v6
	s_mul_i32 s6, s50, 0x160000
	global_load_lds_dwordx4 v154, s[26:27]
	s_add_i32 m0, s38, 0x12000
	v_add_lshl_u32 v128, v9, v8, 1
	s_mul_hi_i32 s5, s50, 0x160000
	s_add_u32 s24, s12, s6
	global_load_lds_dwordx4 v128, s[26:27]
	s_addc_u32 s25, s13, s5
	s_mov_b32 m0, s38
	s_add_i32 s39, s38, 0x2000
	global_load_lds_dwordx4 v154, s[24:25]
	s_mov_b32 m0, s39
	s_add_u32 s6, s26, 0xb0000
	global_load_lds_dwordx4 v128, s[24:25]
	s_addc_u32 s7, s27, 0
	s_add_i32 m0, s38, 0x14000
	s_nop 0
	global_load_lds_dwordx4 v154, s[6:7]
	s_add_i32 m0, s38, 0x16000
	s_nop 0
	global_load_lds_dwordx4 v128, s[6:7]
	s_add_u32 s6, s24, 0xb0000
	s_addc_u32 s7, s25, 0
	s_add_i32 s41, s38, 0x4000
	s_mov_b32 m0, s41
	s_add_i32 s42, s38, 0x6000
	global_load_lds_dwordx4 v154, s[6:7]
	s_mov_b32 m0, s42
	s_cmp_lg_u32 s0, 1
	global_load_lds_dwordx4 v128, s[6:7]
	s_cbranch_scc1 .LBB0_48
	s_barrier

;     __device__ __forceinline__ bool next(int i, Unit& u) const { if (i >= 4) return false; u.pm = pm; u.pn = i; return true; }
;     __device__ __forceinline__ bool next(int i, Unit& u) const {
;         const long L = (long)i * G + c; if (L >= nwg) return false;
;         int wgid = (int)L; { const int q = nwg / NXCD, r = nwg % NXCD, xcd = wgid % NXCD, off = wgid / NXCD; wgid = (xcd < r ? xcd * (q + 1) : r * (q + 1) + (xcd - r) * q) + off; }
;         const int nig = WGM * nN, gid = wgid / nig, fm = gid * WGM, gsz = (nM - fm) < WGM ? (nM - fm) : WGM;
;         u.pm = fm + ((wgid % nig) % gsz); u.pn = (wgid % nig) / gsz; return true;
; template <class Epi, class Sched>
; __device__ __forceinline__ void gemm_phase(LAS unsigned char* lds, const Gemm g, const Sched& S, const Epi& E) {
;     ...
;         const bool has_next = S.next(ui + 1, nxt);
;         const char* nA = has_next ? (const char*)g.A + (size_t)nxt.pm * tstep : cA; const char* nB = has_next ? (const char*)g.Bt + (size_t)nxt.pn * tstep : cB;
.LBB0_54:
	s_ashr_i32 s6, s28, 3
	s_add_i32 s6, s30, s6
	s_xor_b32 s6, s6, 0x7f
	s_ashr_i32 s7, s6, 31
	s_lshr_b32 s7, s7, 27
	s_add_i32 s7, s6, s7
	s_ashr_i32 s28, s7, 5
	s_lshl_b32 s28, s28, 3
	s_sub_i32 s29, 0x100, s28
	s_min_i32 s29, s29, 8
	s_abs_i32 s30, s29
	v_cvt_f32_u32_e32 v0, s30
	s_sub_i32 s48, 0, s30
	s_andn2_b32 s7, s7, 31
	s_sub_i32 s6, s6, s7
	v_rcp_iflag_f32_e32 v0, v0
	s_abs_i32 s7, s6
	s_xor_b32 s31, s6, s29
	s_ashr_i32 s31, s31, 31
	v_mul_f32_e32 v0, 0x4f7ffffe, v0
	v_cvt_u32_f32_e32 v0, v0
	s_nop 0
	v_readfirstlane_b32 s49, v0
	s_mul_i32 s48, s48, s49
	s_mul_hi_u32 s48, s49, s48
	s_add_i32 s49, s49, s48
	s_mul_hi_u32 s48, s7, s49
	s_mul_i32 s49, s48, s30
	s_sub_i32 s7, s7, s49
	s_add_i32 s52, s48, 1
	s_sub_i32 s49, s7, s30
	s_cmp_ge_u32 s7, s30
	s_cselect_b32 s48, s52, s48
	s_cselect_b32 s7, s49, s7
	s_add_i32 s49, s48, 1
	s_cmp_ge_u32 s7, s30
	s_cselect_b32 s7, s49, s48
	s_xor_b32 s7, s7, s31
	s_sub_i32 s48, s7, s31
	s_mul_i32 s7, s48, s29
	s_sub_i32 s6, s6, s7
	s_add_i32 s49, s28, s6

; template <bool KLDS>
; __device__ __forceinline__ void attn_step(const bf16x8 (&kf)[4], LAS const unsigned char* kb, const bf16x8 (&vf)[2][2], const bf16x8 (&qf)[4], f32x16& o0, f32x16& o1, float& m, float& l, int lane, int maskmode) {
;     ...
;     if (maskmode) {
; #pragma unroll
;         for (int i = 0; i < 16; ++i) { const int kr = (i & 3) + 8 * (i >> 2) + 4 * h; const bool ok = (maskmode == 1) ? (kr >= ql) : (kr <= ql); S[i] = ok ? S[i] : -1e30f; }
;     }
.LBB0_274:
	s_andn2_b64 vcc, exec, s[0:1]
	s_cbranch_vccnz .LBB0_276
	s_nop 5
	s_cmp_eq_u32 s86, 0
	s_cbranch_scc0 .LmA_m2
	v_cndmask_b32_e64 v32, v237, v32, s[4:5]
	v_cndmask_b32_e64 v33, v237, v33, s[8:9]
	v_cndmask_b32_e64 v34, v237, v34, s[12:13]
	v_cndmask_b32_e64 v35, v237, v35, s[16:17]
	v_cndmask_b32_e64 v36, v237, v36, s[20:21]
	v_cndmask_b32_e64 v37, v237, v37, s[24:25]
	v_cndmask_b32_e64 v38, v237, v38, s[28:29]
	v_cndmask_b32_e64 v39, v237, v39, s[34:35]
	v_cndmask_b32_e64 v40, v237, v40, s[38:39]
	v_cndmask_b32_e64 v41, v237, v41, s[42:43]
	v_cndmask_b32_e64 v42, v237, v42, s[46:47]
	v_cndmask_b32_e64 v43, v237, v43, s[50:51]
	v_cndmask_b32_e64 v44, v237, v44, s[54:55]
	v_cndmask_b32_e64 v45, v237, v45, s[58:59]
	v_cndmask_b32_e64 v46, v237, v46, s[62:63]
	v_cndmask_b32_e64 v47, v237, v47, s[66:67]
	s_branch .LBB0_276
.LmA_m2:
	v_cndmask_b32_e64 v32, v237, v32, s[6:7]
	v_cndmask_b32_e64 v33, v237, v33, s[10:11]
	v_cndmask_b32_e64 v34, v237, v34, s[14:15]
	v_cndmask_b32_e64 v35, v237, v35, s[18:19]
	v_cndmask_b32_e64 v36, v237, v36, s[22:23]
	v_cndmask_b32_e64 v37, v237, v37, s[26:27]
	v_cndmask_b32_e64 v38, v237, v38, s[30:31]
	v_cndmask_b32_e64 v39, v237, v39, s[36:37]
	v_cndmask_b32_e64 v40, v237, v40, s[40:41]
	v_cndmask_b32_e64 v41, v237, v41, s[44:45]
	v_cndmask_b32_e64 v42, v237, v42, s[48:49]
	v_cndmask_b32_e64 v43, v237, v43, s[52:53]
	v_cndmask_b32_e64 v44, v237, v44, s[56:57]
	v_cndmask_b32_e64 v45, v237, v45, s[60:61]
	v_cndmask_b32_e64 v46, v237, v46, s[64:65]
	v_cndmask_b32_e64 v47, v237, v47, s[68:69]
